# instruction selection: self-max canonicalisations at the head of the row-max trees and the constant alpha test on the DA fast path removed (DA+MLA softmax blocks)
# baseline (speedup 1.0000x reference)
.LBB0_605:
	v_max_f32_e32 v130, v98, v99
	v_max3_f32 v130, v130, v100, v101
	v_max3_f32 v130, v130, v102, v103
	v_max3_f32 v130, v130, v104, v105
	v_max3_f32 v130, v130, v106, v107
	v_max3_f32 v130, v130, v108, v109
	v_max3_f32 v130, v130, v110, v111
	v_max3_f32 v130, v130, v112, v113
	v_max3_f32 v130, v130, v82, v83
	v_max3_f32 v130, v130, v84, v85
	v_max3_f32 v130, v130, v86, v87
	v_max3_f32 v130, v130, v88, v89
	v_max3_f32 v130, v130, v90, v91
	v_max3_f32 v130, v130, v92, v93
	v_max3_f32 v130, v130, v94, v95
	v_max3_f32 v130, v130, v96, v97
	v_mov_b32_e32 v131, v130
	s_nop 1
	v_permlane32_swap_b32_e32 v130, v131
	v_max_f32_e32 v131, v131, v131
	v_max_f32_e32 v130, v130, v130
	v_max_f32_e32 v130, v130, v131
	v_cmp_ge_f32_e32 vcc, s76, v130
	s_cmp_eq_u64 vcc, exec
	v_mov_b32_e32 v194, 1.0
	s_cbranch_scc0 .LBB0_627
	s_branch .LBB0_610

.LBB0_618:
	v_max_f32_e32 v130, v98, v99
	v_max3_f32 v130, v130, v100, v101
	v_max3_f32 v130, v130, v102, v103
	v_max3_f32 v130, v130, v104, v105
	v_max3_f32 v130, v130, v106, v107
	v_max3_f32 v130, v130, v108, v109
	v_max3_f32 v130, v130, v110, v111
	v_max3_f32 v130, v130, v112, v113
	v_max3_f32 v130, v130, v82, v83
	v_max3_f32 v130, v130, v84, v85
	v_max3_f32 v130, v130, v86, v87
	v_max3_f32 v130, v130, v88, v89
	v_max3_f32 v130, v130, v90, v91
	v_max3_f32 v130, v130, v92, v93
	v_max3_f32 v130, v130, v94, v95
	v_max3_f32 v130, v130, v96, v97
	v_mov_b32_e32 v131, v130
	s_nop 1
	v_permlane32_swap_b32_e32 v130, v131
	v_max_f32_e32 v131, v131, v131
	v_max_f32_e32 v130, v130, v130
	v_max_f32_e32 v130, v130, v131
	v_cmp_ge_f32_e32 vcc, s76, v130
	s_cmp_eq_u64 vcc, exec
	v_mov_b32_e32 v197, 1.0
	s_cbranch_scc0 .LBB0_628
	s_branch .LBB0_623

.LBB0_631:
	v_max_f32_e32 v98, v82, v83
	v_max3_f32 v98, v98, v84, v85
	v_max3_f32 v98, v98, v86, v87
	v_max3_f32 v98, v98, v88, v89
	v_max3_f32 v98, v98, v90, v91
	v_max3_f32 v98, v98, v92, v93
	v_max3_f32 v98, v98, v94, v95
	v_max3_f32 v98, v98, v96, v97
	v_max3_f32 v98, v98, v66, v67
	v_max3_f32 v98, v98, v68, v69
	v_max3_f32 v98, v98, v70, v71
	v_max3_f32 v98, v98, v72, v73
	v_max3_f32 v98, v98, v74, v75
	v_max3_f32 v98, v98, v76, v77
	v_max3_f32 v98, v98, v78, v79
	v_max3_f32 v98, v98, v80, v81
	v_mov_b32_e32 v99, v98
	s_nop 1
	v_permlane32_swap_b32_e32 v98, v99
	v_max_f32_e32 v99, v99, v99
	v_max_f32_e32 v98, v98, v98
	v_max_f32_e32 v98, v98, v99
	v_cmp_ge_f32_e32 vcc, s76, v98
	s_cmp_eq_u64 vcc, exec
	v_mov_b32_e32 v114, 1.0
	s_barrier
	s_cbranch_scc0 .LBB0_642
	v_cmp_gt_f32_e32 vcc, 1.0, v114
	s_cbranch_vccz .LBB0_636

.LBB0_658:
	s_nop 0
	v_max_f32_e32 v2, v34, v35
	v_max3_f32 v2, v2, v36, v37
	v_max3_f32 v2, v2, v38, v39
	v_max3_f32 v2, v2, v40, v41
	v_max3_f32 v2, v2, v42, v43
	v_max3_f32 v2, v2, v44, v45
	v_max3_f32 v2, v2, v46, v47
	v_max3_f32 v2, v2, v48, v49
	v_max3_f32 v2, v2, v18, v19
	v_max3_f32 v2, v2, v20, v21
	v_max3_f32 v2, v2, v22, v23
	v_max3_f32 v2, v2, v24, v25
	v_max3_f32 v2, v2, v26, v27
	v_max3_f32 v2, v2, v28, v29
	v_max3_f32 v2, v2, v30, v31
	v_max3_f32 v2, v2, v32, v33
	v_mov_b32_e32 v3, v2
	s_nop 1
	v_permlane32_swap_b32_e32 v2, v3
	v_max_f32_e32 v3, v3, v3
	v_max_f32_e32 v2, v2, v2
	v_max_f32_e32 v2, v2, v3
	s_and_b32 s0, s2, 0x3fffffc0
	v_max_f32_e32 v59, 0xf149f2ca, v2
	s_lshl_b32 s0, s0, 2
	v_add_f32_e32 v3, 0x7149f2ca, v2
	v_sub_f32_e32 v2, 0xf149f2ca, v59
	s_add_i32 s18, s0, 0
	v_exp_f32_e32 v2, v2
	s_add_i32 s18, s18, 0x18000
	v_cmp_ge_f32_e32 vcc, s80, v3
	s_cmp_eq_u64 vcc, exec
	s_cselect_b64 s[2:3], -1, 0
	v_cndmask_b32_e64 v58, v2, 1.0, s[2:3]
	v_cmp_gt_f32_e32 vcc, 1.0, v58
	v_cmp_gt_u32_e64 s[0:1], 32, v50
	s_cbranch_vccz .LBB0_662
	s_and_saveexec_b64 s[56:57], s[0:1]
	v_lshl_add_u32 v2, v54, 2, s18
	ds_write_b32 v2, v58 offset:128
	s_or_b64 exec, exec, s[56:57]
	s_waitcnt lgkmcnt(0)
	v_lshl_add_u32 v10, v55, 4, s18
	ds_read_b128 v[2:5], v10 offset:224
	ds_read_b128 v[6:9], v10 offset:192
	ds_read_b128 v[60:63], v10 offset:160
	ds_read_b128 v[64:67], v10 offset:128
	s_waitcnt lgkmcnt(0)
	v_pk_mul_f32 v[16:17], v[4:5], 0 op_sel_hi:[1,0]
	v_pk_mul_f32 v[12:13], v[8:9], 0 op_sel_hi:[1,0]
	v_pk_mul_f32 v[8:9], v[62:63], 0 op_sel_hi:[1,0]
	v_pk_mul_f32 v[4:5], v[66:67], 0 op_sel_hi:[1,0]
	v_pk_mul_f32 v[14:15], v[2:3], 0 op_sel_hi:[1,0]
	v_pk_mul_f32 v[10:11], v[6:7], 0 op_sel_hi:[1,0]
	v_pk_mul_f32 v[6:7], v[60:61], 0 op_sel_hi:[1,0]
	v_pk_mul_f32 v[2:3], v[64:65], 0 op_sel_hi:[1,0]
	s_branch .LBB0_663

.LBB0_672:
	v_max_f32_e32 v118, v82, v83
	v_max3_f32 v118, v118, v84, v85
	v_max3_f32 v118, v118, v86, v87
	v_max3_f32 v118, v118, v88, v89
	v_max3_f32 v118, v118, v90, v91
	v_max3_f32 v118, v118, v92, v93
	v_max3_f32 v118, v118, v94, v95
	v_max3_f32 v118, v118, v96, v97
	v_max3_f32 v118, v118, v66, v67
	v_max3_f32 v118, v118, v68, v69
	v_max3_f32 v118, v118, v70, v71
	v_max3_f32 v118, v118, v72, v73
	v_max3_f32 v118, v118, v74, v75
	v_max3_f32 v118, v118, v76, v77
	v_max3_f32 v118, v118, v78, v79
	v_max3_f32 v118, v118, v80, v81
	v_mov_b32_e32 v119, v118
	s_nop 1
	v_permlane32_swap_b32_e32 v118, v119
	v_max_f32_e32 v119, v119, v119
	v_max_f32_e32 v118, v118, v118
	v_max_f32_e32 v118, v118, v119
	v_max_f32_e32 v120, v186, v186
	v_sub_f32_e32 v119, v118, v186
	v_max_f32_e32 v118, v120, v118
	v_sub_f32_e32 v120, v186, v118
	v_exp_f32_e32 v120, v120
	v_cmp_ge_f32_e32 vcc, s80, v119
	s_cmp_eq_u64 vcc, exec
	s_cselect_b64 s[8:9], -1, 0
	v_cndmask_b32_e64 v201, v120, 1.0, s[8:9]
	v_cmp_gt_f32_e32 vcc, 1.0, v201
	s_cbranch_vccz .LBB0_676
	s_and_saveexec_b64 s[56:57], s[4:5]
	ds_write_b32 v157, v201 offset:128
	s_or_b64 exec, exec, s[56:57]
	s_waitcnt lgkmcnt(0)
	v_add_u32_e32 v119, s18, v156
	ds_read_b128 v[120:123], v119 offset:128
	ds_read_b128 v[124:127], v119 offset:160
	ds_read_b128 v[128:131], v119 offset:192
	ds_read_b128 v[202:205], v119 offset:224
	s_waitcnt lgkmcnt(0)
	v_pk_mul_f32 v[34:35], v[120:121], v[34:35]
	v_pk_mul_f32 v[36:37], v[36:37], v[122:123]
	v_pk_mul_f32 v[38:39], v[38:39], v[124:125]
	v_pk_mul_f32 v[40:41], v[40:41], v[126:127]
	v_pk_mul_f32 v[42:43], v[42:43], v[128:129]
	v_pk_mul_f32 v[44:45], v[44:45], v[130:131]
	v_pk_mul_f32 v[46:47], v[46:47], v[202:203]
	v_pk_mul_f32 v[62:63], v[62:63], v[202:203]
	v_pk_mul_f32 v[58:59], v[58:59], v[128:129]
	v_pk_mul_f32 v[54:55], v[54:55], v[124:125]
	v_pk_mul_f32 v[64:65], v[64:65], v[204:205]
	v_pk_mul_f32 v[60:61], v[60:61], v[130:131]
	v_pk_mul_f32 v[56:57], v[56:57], v[126:127]
	v_pk_mul_f32 v[52:53], v[52:53], v[122:123]
	v_pk_mul_f32 v[50:51], v[50:51], v[120:121]
	v_pk_mul_f32 v[48:49], v[48:49], v[204:205]
	v_pk_mul_f32 v[2:3], v[120:121], v[2:3]
	v_pk_mul_f32 v[4:5], v[4:5], v[122:123]
	v_pk_mul_f32 v[6:7], v[6:7], v[124:125]
	v_pk_mul_f32 v[8:9], v[8:9], v[126:127]
	v_pk_mul_f32 v[10:11], v[10:11], v[128:129]
	v_pk_mul_f32 v[12:13], v[12:13], v[130:131]
	v_pk_mul_f32 v[14:15], v[14:15], v[202:203]
	v_pk_mul_f32 v[30:31], v[30:31], v[202:203]
	v_pk_mul_f32 v[26:27], v[26:27], v[128:129]
	v_pk_mul_f32 v[22:23], v[22:23], v[124:125]
	v_pk_mul_f32 v[32:33], v[32:33], v[204:205]
	v_pk_mul_f32 v[28:29], v[28:29], v[130:131]
	v_pk_mul_f32 v[24:25], v[24:25], v[126:127]
	v_pk_mul_f32 v[20:21], v[20:21], v[122:123]
	v_pk_mul_f32 v[18:19], v[18:19], v[120:121]
	v_pk_mul_f32 v[16:17], v[16:17], v[204:205]

.LBB0_684:
	v_max_f32_e32 v118, v82, v83
	v_max3_f32 v118, v118, v84, v85
	v_max3_f32 v118, v118, v86, v87
	v_max3_f32 v118, v118, v88, v89
	v_max3_f32 v118, v118, v90, v91
	v_max3_f32 v118, v118, v92, v93
	v_max3_f32 v118, v118, v94, v95
	v_max3_f32 v118, v118, v96, v97
	v_max3_f32 v118, v118, v66, v67
	v_max3_f32 v118, v118, v68, v69
	v_max3_f32 v118, v118, v70, v71
	v_max3_f32 v118, v118, v72, v73
	v_max3_f32 v118, v118, v74, v75
	v_max3_f32 v118, v118, v76, v77
	v_max3_f32 v118, v118, v78, v79
	v_max3_f32 v118, v118, v80, v81
	v_mov_b32_e32 v119, v118
	s_nop 1
	v_permlane32_swap_b32_e32 v118, v119
	v_max_f32_e32 v119, v119, v119
	v_max_f32_e32 v118, v118, v118
	v_max_f32_e32 v118, v118, v119
	v_max_f32_e32 v120, v186, v186
	v_sub_f32_e32 v119, v118, v186
	v_max_f32_e32 v118, v120, v118
	v_sub_f32_e32 v120, v186, v118
	v_exp_f32_e32 v120, v120
	v_cmp_ge_f32_e32 vcc, s80, v119
	s_cmp_eq_u64 vcc, exec
	s_cselect_b64 s[8:9], -1, 0
	v_cndmask_b32_e64 v204, v120, 1.0, s[8:9]
	v_cmp_gt_f32_e32 vcc, 1.0, v204
	s_cbranch_vccz .LBB0_688
	s_and_saveexec_b64 s[58:59], s[4:5]
	ds_write_b32 v157, v204 offset:128
	s_or_b64 exec, exec, s[58:59]
	s_waitcnt lgkmcnt(0)
	v_add_u32_e32 v119, s18, v156
	ds_read_b128 v[120:123], v119 offset:128
	ds_read_b128 v[124:127], v119 offset:160
	ds_read_b128 v[128:131], v119 offset:192
	ds_read_b128 v[206:209], v119 offset:224
	s_waitcnt lgkmcnt(0)
	v_pk_mul_f32 v[34:35], v[120:121], v[34:35]
	v_pk_mul_f32 v[36:37], v[36:37], v[122:123]
	v_pk_mul_f32 v[38:39], v[38:39], v[124:125]
	v_pk_mul_f32 v[40:41], v[40:41], v[126:127]
	v_pk_mul_f32 v[42:43], v[42:43], v[128:129]
	v_pk_mul_f32 v[44:45], v[44:45], v[130:131]
	v_pk_mul_f32 v[46:47], v[46:47], v[206:207]
	v_pk_mul_f32 v[62:63], v[62:63], v[206:207]
	v_pk_mul_f32 v[58:59], v[58:59], v[128:129]
	v_pk_mul_f32 v[54:55], v[54:55], v[124:125]
	v_pk_mul_f32 v[64:65], v[64:65], v[208:209]
	v_pk_mul_f32 v[60:61], v[60:61], v[130:131]
	v_pk_mul_f32 v[56:57], v[56:57], v[126:127]
	v_pk_mul_f32 v[52:53], v[52:53], v[122:123]
	v_pk_mul_f32 v[50:51], v[50:51], v[120:121]
	v_pk_mul_f32 v[48:49], v[48:49], v[208:209]
	v_pk_mul_f32 v[2:3], v[120:121], v[2:3]
	v_pk_mul_f32 v[4:5], v[4:5], v[122:123]
	v_pk_mul_f32 v[6:7], v[6:7], v[124:125]
	v_pk_mul_f32 v[8:9], v[8:9], v[126:127]
	v_pk_mul_f32 v[10:11], v[10:11], v[128:129]
	v_pk_mul_f32 v[12:13], v[12:13], v[130:131]
	v_pk_mul_f32 v[14:15], v[14:15], v[206:207]
	v_pk_mul_f32 v[30:31], v[30:31], v[206:207]
	v_pk_mul_f32 v[26:27], v[26:27], v[128:129]
	v_pk_mul_f32 v[22:23], v[22:23], v[124:125]
	v_pk_mul_f32 v[32:33], v[32:33], v[208:209]
	v_pk_mul_f32 v[28:29], v[28:29], v[130:131]
	v_pk_mul_f32 v[24:25], v[24:25], v[126:127]
	v_pk_mul_f32 v[20:21], v[20:21], v[122:123]
	v_pk_mul_f32 v[18:19], v[18:19], v[120:121]
	v_pk_mul_f32 v[16:17], v[16:17], v[208:209]
